# in-proj per-tile scheduler: generic x/gsz division (v_rcp + readfirstlane + SALU refinement) strength-reduced to a shift (gsz is always 8)
# speedup vs baseline: 1.0001x; 1.0001x over previous
; __device__ __forceinline__ bool tile_order(long L, int nM, int nN, int& pm, int& pn) {
;     const int nwg = nM * nN; if (L >= nwg) return false;
;     int wgid = (int)L; { const int q = nwg / NXCD, r = nwg % NXCD, xcd = wgid % NXCD, off = wgid / NXCD; wgid = (xcd < r ? xcd * (q + 1) : r * (q + 1) + (xcd - r) * q) + off; }
;     const int nig = WGM * nN, gid = wgid / nig, fm = gid * WGM, gsz = (nM - fm) < WGM ? (nM - fm) : WGM;
;     pm = fm + ((wgid % nig) % gsz); pn = (wgid % nig) / gsz; return true;
; }
;     __device__ __forceinline__ bool next(int i, pg8::Unit& u) const {
;         if (!pg8::tile_order((long)i * G + c, T_TOK / 256, NIN / 256, u.pm, u.pn)) return false;
;         u.a = (const char*)(A + (size_t)u.pm * 256 * DM); u.b = (const char*)(Bt + (size_t)u.pn * 256 * DM); u.sub = 0; return true;
.LBB0_98:
	s_add_i32 s73, s73, 1
	s_mul_i32 s2, s73, s74
	s_mul_hi_u32 s3, s73, s54
	s_add_i32 s3, s3, s2
	s_mul_i32 s2, s73, s54
	s_add_u32 s46, s2, s10
	s_addc_u32 s47, s3, s11
	v_mov_b64_e32 v[0:1], 0xe7f
	v_cmp_gt_i64_e64 s[2:3], s[46:47], v[0:1]
	s_and_b64 vcc, exec, s[2:3]
	s_mov_b64 s[12:13], s[44:45]
	s_mov_b64 s[4:5], s[40:41]
	s_cbranch_vccnz .LBB0_100
	s_ashr_i32 s4, s46, 31
	s_lshr_b32 s4, s4, 29
	s_add_i32 s4, s46, s4
	s_ashr_i32 s5, s4, 3
	s_and_b32 s4, s4, -8
	s_sub_i32 s4, s46, s4
	s_lshr_b32 s8, s4, 31
	s_or_b32 s8, s8, 0x1d0
	s_mul_i32 s4, s8, s4
	s_add_i32 s4, s4, s5
	s_mul_hi_i32 s5, s4, 0x8d3dcb09
	s_add_i32 s5, s5, s4
	s_lshr_b32 s8, s5, 31
	s_ashr_i32 s5, s5, 8
	s_add_i32 s5, s5, s8
	s_lshl_b32 s9, s5, 3
	s_sub_i32 s8, 64, s9
	s_min_i32 s12, s8, 8
	s_mulk_i32 s5, 0x1d0
	s_sub_i32 s4, s4, s5
	s_ashr_i32 s8, s4, 3
	s_mul_i32 s5, s8, s12
	s_sub_i32 s4, s4, s5
	s_add_i32 s82, s4, s9
	s_ashr_i32 s83, s82, 31
	s_lshl_b64 s[4:5], s[82:83], 20
	s_add_u32 s4, s20, s4
	s_addc_u32 s5, s21, s5
	s_ashr_i32 s9, s8, 31
	s_lshl_b64 s[12:13], s[8:9], 20
	s_add_u32 s12, s52, s12
	s_addc_u32 s13, s53, s13
	s_mov_b64 s[42:43], s[12:13]
	s_mov_b64 s[94:95], s[4:5]
